# NSA compress phase 1: A/W1 chunks staged through LDS with coalesced loads (double buffered, one barrier per 128-k chunk), same MFMA order
# speedup vs baseline: 1.0141x; 1.0141x over previous
; DI f32x16 mfma32(bf16x8 a, bf16x8 b, f32x16 c) { return __builtin_amdgcn_mfma_f32_32x32x16_bf16(a, b, c, 0, 0, 0); }
; DI f32x16 zero16() { f32x16 z; for (int i = 0; i < 16; ++i) z[i] = 0.f; return z; }
; DI void nsa_compress_phase(int wv, LAS unsigned char* lds, const bf16_t* slab  , const bf16_t* wn  , const float* c1  , bf16_t* KCMP, bf16_t* VCMPT) {
;     ...
;         const int b = item >> 4, g = (item >> 2) & 3, kv = (item >> 1) & 1, nh = item & 1;
;         const bf16_t* src = slab + (size_t)kv * SLAB_EL + (size_t)(b * 4 + g) * 2048 * 64;
;         const bf16_t* w1t = wn + (kv ? NSA_W1V : NSA_W1K); const bf16_t* w2t = wn + (kv ? NSA_W2V : NSA_W2K);
;         {
;             const int rh = w >> 2, cq = w & 3;
;             int n = 64 * nh + 32 * rh + r; if (n > 126) n = 126;
;             const bf16_t* ap = src + (size_t)n * 1024 + 8 * hh;
;             const bf16_t* bp = w1t + (size_t)(32 * cq + r) * 2048 + 8 * hh;
;             f32x16 acc = zero16();
; #pragma unroll 8
;             for (int ks = 0; ks < 128; ++ks) {
;                 const bf16x8 xa = *(const bf16x8*)(ap + 16 * ks), wb = *(const bf16x8*)(bp + 16 * ks);
;                 acc = mfma32(wb, xa, acc);
;             }
.LBB0_2145:
	s_and_b32 s4, s0, 64
	v_add_u32_e32 v2, s4, v66
	v_ashrrev_i32_e32 v3, 31, v2
	s_mov_b64 s[4:5], 0x7e
	s_bfe_u32 s18, s1, 0x10001
	v_cmp_gt_i64_e32 vcc, s[4:5], v[2:3]
	s_ashr_i32 s4, s1, 2
	s_lshl_b32 s19, s18, 24
	s_lshr_b32 s16, s1, 2
	s_bfe_u32 s20, s1, 0x20002
	s_and_b32 s17, s4, -4
	s_bitcmp1_b32 s1, 1
	s_cselect_b64 s[12:13], -1, 0
	s_cmp_eq_u32 s18, 0
	s_cselect_b64 s[4:5], -1, 0
	s_and_b64 s[14:15], s[4:5], exec
	s_mov_b32 s14, 0x580000
	s_cselect_b32 s96, s14, 0x600000
	s_or_b32 s14, s17, s20
	s_ashr_i32 s15, s14, 31
	v_mov_b32_e32 v4, 0x7e
	s_lshl_b64 s[14:15], s[14:15], 18
	v_cndmask_b32_e32 v3, 0, v3, vcc
	v_cndmask_b32_e32 v2, v4, v2, vcc
	s_add_u32 s14, s19, s14
	v_lshlrev_b64 v[2:3], 11, v[2:3]
	s_addc_u32 s15, 0, s15
	v_lshl_add_u64 v[2:3], s[14:15], 0, v[2:3]
	s_mov_b64 s[26:27], s[14:15]
	s_and_b32 s46, s0, 64
	v_lshl_add_u64 v[18:19], v[60:61], 0, v[2:3]
	v_mov_b32_e32 v2, 0
	v_lshl_add_u64 v[20:21], v[62:63], 0, s[96:97]
	s_mov_b64 s[14:15], 0
	v_mov_b32_e32 v3, v2
	v_mov_b32_e32 v4, v2
	v_mov_b32_e32 v5, v2
	v_mov_b32_e32 v6, v2
	v_mov_b32_e32 v7, v2
	v_mov_b32_e32 v8, v2
	v_mov_b32_e32 v9, v2
	v_mov_b32_e32 v10, v2
	v_mov_b32_e32 v11, v2
	v_mov_b32_e32 v12, v2
	v_mov_b32_e32 v13, v2
	v_mov_b32_e32 v14, v2
	v_mov_b32_e32 v15, v2
	v_mov_b32_e32 v16, v2
	v_mov_b32_e32 v17, v2
.LBB0_2146:
	s_add_u32 s26, s26, s74
	s_addc_u32 s27, s27, s75
	s_add_u32 s26, s26, 0x12600000
	s_addc_u32 s27, s27, 0
	v_readlane_b32 s28, v255, 39
	v_readlane_b32 s29, v255, 38
	s_add_u32 s28, s28, s74
	s_addc_u32 s29, s29, s75
	s_add_u32 s28, s28, s96
	s_addc_u32 s29, s29, 0
	s_add_u32 s28, s28, 0xd440000
	s_addc_u32 s29, s29, 0
	s_mov_b32 s19, -1
	v_mbcnt_lo_u32_b32 v22, s19, 0
	v_mbcnt_hi_u32_b32 v22, s19, v22
	v_add_u32_e32 v22, s11, v22
	v_lshrrev_b32_e32 v23, 4, v22
	v_and_b32_e32 v30, 15, v22
	v_lshlrev_b32_e32 v30, 4, v30
	v_add_u32_e32 v31, s46, v23
	v_add_u32_e32 v32, 32, v31
	v_min_u32_e32 v31, 0x7e, v31
	v_min_u32_e32 v32, 0x7e, v32
	v_lshl_add_u32 v236, v31, 11, v30
	v_lshl_add_u32 v237, v32, 11, v30
	v_lshl_add_u32 v238, v23, 12, v30
	v_add_u32_e32 v239, 0x20000, v238
	v_add_u32_e32 v240, 0x40000, v238
	v_add_u32_e32 v241, 0x60000, v238
	s_movk_i32 s19, 0x110
	v_mad_u32_u24 v242, v23, s19, v30
	v_and_b32_e32 v31, 31, v22
	v_bfe_u32 v32, v22, 5, 1
	v_lshlrev_b32_e32 v32, 4, v32
	v_lshrrev_b32_e32 v33, 8, v22
	v_lshl_add_u32 v33, v33, 5, v31
	v_mad_u32_u24 v243, v33, s19, v32
	v_bfe_u32 v33, v22, 6, 2
	v_lshl_add_u32 v33, v33, 5, v31
	v_mad_u32_u24 v244, v33, s19, v32
	v_add_u32_e32 v244, 0x4400, v244
	global_load_dwordx4 v[80:83], v236, s[26:27]
	global_load_dwordx4 v[84:87], v237, s[26:27]
	global_load_dwordx4 v[88:91], v238, s[28:29]
	global_load_dwordx4 v[92:95], v239, s[28:29]
	global_load_dwordx4 v[96:99], v240, s[28:29]
	global_load_dwordx4 v[100:103], v241, s[28:29]
	s_mov_b32 s14, 0
	s_mov_b32 s45, 0xcc00
.Lcmp_chunk:
	s_waitcnt vmcnt(0)
	ds_write_b128 v242, v[80:83]
	ds_write_b128 v242, v[84:87] offset:8704
	ds_write_b128 v242, v[88:91] offset:17408
	ds_write_b128 v242, v[92:95] offset:26112
	ds_write_b128 v242, v[96:99] offset:34816
	ds_write_b128 v242, v[100:103] offset:43520
	s_add_u32 s26, s26, 0x100
	s_addc_u32 s27, s27, 0
	s_add_u32 s28, s28, 0x100
	s_addc_u32 s29, s29, 0
	s_cmp_eq_u32 s14, 15
	s_cbranch_scc1 .Lcmp_noload
	global_load_dwordx4 v[80:83], v236, s[26:27]
	global_load_dwordx4 v[84:87], v237, s[26:27]
	global_load_dwordx4 v[88:91], v238, s[28:29]
	global_load_dwordx4 v[92:95], v239, s[28:29]
	global_load_dwordx4 v[96:99], v240, s[28:29]
	global_load_dwordx4 v[100:103], v241, s[28:29]
.Lcmp_noload:
	s_waitcnt lgkmcnt(0)
	s_barrier
	ds_read_b128 v[104:107], v243
	ds_read_b128 v[164:167], v244
	ds_read_b128 v[108:111], v243 offset:32
	ds_read_b128 v[168:171], v244 offset:32
	ds_read_b128 v[112:115], v243 offset:64
	ds_read_b128 v[172:175], v244 offset:64
	ds_read_b128 v[116:119], v243 offset:96
	ds_read_b128 v[176:179], v244 offset:96
	ds_read_b128 v[120:123], v243 offset:128
	ds_read_b128 v[180:183], v244 offset:128
	ds_read_b128 v[124:127], v243 offset:160
	ds_read_b128 v[184:187], v244 offset:160
	ds_read_b128 v[128:131], v243 offset:192
	ds_read_b128 v[188:191], v244 offset:192
	ds_read_b128 v[132:135], v243 offset:224
	ds_read_b128 v[192:195], v244 offset:224
	s_waitcnt lgkmcnt(14)
	v_mfma_f32_32x32x16_bf16 v[2:17], v[164:167], v[104:107], v[2:17]
	s_waitcnt lgkmcnt(12)
	v_mfma_f32_32x32x16_bf16 v[2:17], v[168:171], v[108:111], v[2:17]
	s_waitcnt lgkmcnt(10)
	v_mfma_f32_32x32x16_bf16 v[2:17], v[172:175], v[112:115], v[2:17]
	s_waitcnt lgkmcnt(8)
	v_mfma_f32_32x32x16_bf16 v[2:17], v[176:179], v[116:119], v[2:17]
	s_waitcnt lgkmcnt(6)
	v_mfma_f32_32x32x16_bf16 v[2:17], v[180:183], v[120:123], v[2:17]
	s_waitcnt lgkmcnt(4)
	v_mfma_f32_32x32x16_bf16 v[2:17], v[184:187], v[124:127], v[2:17]
	s_waitcnt lgkmcnt(2)
	v_mfma_f32_32x32x16_bf16 v[2:17], v[188:191], v[128:131], v[2:17]
	s_waitcnt lgkmcnt(0)
	v_mfma_f32_32x32x16_bf16 v[2:17], v[192:195], v[132:135], v[2:17]
	v_add_u32_e32 v242, s45, v242
	v_add_u32_e32 v243, s45, v243
	v_add_u32_e32 v244, s45, v244
	s_sub_i32 s45, 0, s45
	s_add_i32 s14, s14, 1
	s_cmp_lt_u32 s14, 16
	s_cbranch_scc1 .Lcmp_chunk
; #define LAS __attribute__((address_space(3)))
; DI float sigmoidf_(float x) { return frcp(1.f + fexp2(-x * LOG2E)); }
; DI f32x16 mfma32(bf16x8 a, bf16x8 b, f32x16 c) { return __builtin_amdgcn_mfma_f32_32x32x16_bf16(a, b, c, 0, 0, 0); }
; DI f32x16 zero16() { f32x16 z; for (int i = 0; i < 16; ++i) z[i] = 0.f; return z; }
; DI void nsa_compress_phase(int wv, LAS unsigned char* lds, const bf16_t* slab  , const bf16_t* wn  , const float* c1  , bf16_t* KCMP, bf16_t* VCMPT) {
;     ...
;             const float* cb = c1 + kv * 128;
; #pragma unroll
;             for (int gq = 0; gq < 4; ++gq) {
;                 float v[4];
; #pragma unroll
;                 for (int e = 0; e < 4; ++e) { const int j = 32 * cq + 8 * gq + 4 * hh + e; const float x = acc[4 * gq + e] + cb[j];
;                     const float u2 = 2.f * 0.7978845608028654f * (x + 0.044715f * x * x * x); v[e] = x * sigmoidf_(u2); }
;                 u32x2 wv; wv.x = pk2(v[0], v[1]); wv.y = pk2(v[2], v[3]);
;                 *(LAS u32x2*)(lds + (32 * rh + r) * HS + (32 * cq + 8 * gq + 4 * hh) * 2) = wv;
;             }
;         }
;         __syncthreads();
;         if (w < 4) {
;             const int rh2 = w >> 1, dq = w & 1;
;             f32x16 acc = zero16();
; #pragma unroll
;             for (int ks = 0; ks < 8; ++ks) {
;                 const bf16x8 hf = *(const LAS bf16x8*)(lds + (32 * rh2 + r) * HS + (16 * ks + 8 * hh) * 2);
;                 const bf16x8 wf = *(const bf16x8*)(w2t + (size_t)(32 * dq + r) * 128 + 16 * ks + 8 * hh);
;                 if (kv == 0) acc = mfma32(wf, hf, acc);
	s_nop 1
	s_lshl_b32 s96, s18, 9
	v_lshl_add_u64 v[22:23], v[58:59], 0, s[96:97]
	flat_load_dwordx4 v[18:21], v[22:23]
	s_and_b64 vcc, exec, s[6:7]
	s_waitcnt vmcnt(0) lgkmcnt(0)
	s_nop 5
	v_pk_add_f32 v[2:3], v[2:3], v[18:19]
	v_pk_add_f32 v[4:5], v[4:5], v[20:21]
	v_mul_f32_e32 v18, 0x3d372713, v2
	v_mul_f32_e32 v19, 0x3d372713, v3
	v_mul_f32_e32 v20, 0x3d372713, v4
	v_mul_f32_e32 v21, 0x3d372713, v5
	v_mul_f32_e32 v18, v2, v18
	v_mul_f32_e32 v19, v3, v19
	v_mul_f32_e32 v20, v4, v20
	v_mul_f32_e32 v21, v5, v21
	v_fma_f32 v18, v2, v18, v2
	v_fma_f32 v19, v3, v19, v3
	v_fma_f32 v20, v4, v20, v4
	v_fma_f32 v21, v5, v21, v5
	v_mul_f32_e32 v18, 0x3fcc422a, v18
	v_mul_f32_e32 v19, 0x3fcc422a, v19
	v_mul_f32_e32 v20, 0x3fcc422a, v20
	v_mul_f32_e32 v21, 0x3fcc422a, v21
	v_mul_f32_e32 v18, 0xbfb8aa3b, v18
	v_mul_f32_e32 v19, 0xbfb8aa3b, v19
	v_mul_f32_e32 v20, 0xbfb8aa3b, v20
	v_mul_f32_e32 v21, 0xbfb8aa3b, v21
	v_exp_f32_e32 v18, v18
	v_exp_f32_e32 v19, v19
	v_exp_f32_e32 v20, v20
	v_exp_f32_e32 v21, v21
	v_add_f32_e32 v18, 1.0, v18
	v_add_f32_e32 v19, 1.0, v19
	v_add_f32_e32 v20, 1.0, v20
	v_add_f32_e32 v21, 1.0, v21
	v_rcp_f32_e32 v18, v18
	v_rcp_f32_e32 v19, v19
	v_rcp_f32_e32 v20, v20
	v_rcp_f32_e32 v21, v21
	v_pk_mul_f32 v[2:3], v[2:3], v[18:19]
	s_nop 0
	v_cvt_pk_bf16_f32 v2, v2, v3
	v_pk_mul_f32 v[4:5], v[4:5], v[20:21]
	s_nop 0
	v_cvt_pk_bf16_f32 v3, v4, v5
	ds_write_b64 v67, v[2:3]
	flat_load_dwordx4 v[2:5], v[22:23] offset:32
	s_waitcnt vmcnt(0) lgkmcnt(0)
	v_pk_add_f32 v[2:3], v[6:7], v[2:3]
	v_pk_add_f32 v[4:5], v[8:9], v[4:5]
	v_mul_f32_e32 v6, 0x3d372713, v2
	v_mul_f32_e32 v7, 0x3d372713, v3
	v_mul_f32_e32 v8, 0x3d372713, v4
	v_mul_f32_e32 v9, 0x3d372713, v5
	v_mul_f32_e32 v6, v2, v6
	v_mul_f32_e32 v7, v3, v7
	v_mul_f32_e32 v8, v4, v8
	v_mul_f32_e32 v9, v5, v9
	v_fma_f32 v6, v2, v6, v2
	v_fma_f32 v7, v3, v7, v3
	v_fma_f32 v8, v4, v8, v4
	v_fma_f32 v9, v5, v9, v5
	v_mul_f32_e32 v6, 0x3fcc422a, v6
	v_mul_f32_e32 v7, 0x3fcc422a, v7
	v_mul_f32_e32 v8, 0x3fcc422a, v8
	v_mul_f32_e32 v9, 0x3fcc422a, v9
	v_mul_f32_e32 v6, 0xbfb8aa3b, v6
	v_mul_f32_e32 v7, 0xbfb8aa3b, v7
	v_mul_f32_e32 v8, 0xbfb8aa3b, v8
	v_mul_f32_e32 v9, 0xbfb8aa3b, v9
	v_exp_f32_e32 v6, v6
	v_exp_f32_e32 v7, v7
	v_exp_f32_e32 v8, v8
	v_exp_f32_e32 v9, v9
	v_add_f32_e32 v6, 1.0, v6
	v_add_f32_e32 v7, 1.0, v7
	v_add_f32_e32 v8, 1.0, v8
	v_add_f32_e32 v9, 1.0, v9
	v_rcp_f32_e32 v6, v6
	v_rcp_f32_e32 v7, v7
	v_rcp_f32_e32 v8, v8
	v_rcp_f32_e32 v9, v9
	v_pk_mul_f32 v[2:3], v[2:3], v[6:7]
	s_nop 0
	v_cvt_pk_bf16_f32 v2, v2, v3
	v_pk_mul_f32 v[4:5], v[4:5], v[8:9]
	s_nop 0
	v_cvt_pk_bf16_f32 v3, v4, v5
	ds_write_b64 v67, v[2:3] offset:16
	flat_load_dwordx4 v[2:5], v[22:23] offset:64
	s_waitcnt vmcnt(0) lgkmcnt(0)
	v_pk_add_f32 v[2:3], v[10:11], v[2:3]
	v_pk_add_f32 v[4:5], v[12:13], v[4:5]
	v_mul_f32_e32 v6, 0x3d372713, v2
	v_mul_f32_e32 v7, 0x3d372713, v3
	v_mul_f32_e32 v8, 0x3d372713, v4
	v_mul_f32_e32 v9, 0x3d372713, v5
	v_mul_f32_e32 v6, v2, v6
	v_mul_f32_e32 v7, v3, v7
	v_mul_f32_e32 v8, v4, v8
	v_mul_f32_e32 v9, v5, v9
	v_fma_f32 v6, v2, v6, v2
	v_fma_f32 v7, v3, v7, v3
	v_fma_f32 v8, v4, v8, v4
	v_fma_f32 v9, v5, v9, v5
	v_mul_f32_e32 v6, 0x3fcc422a, v6
	v_mul_f32_e32 v7, 0x3fcc422a, v7
	v_mul_f32_e32 v8, 0x3fcc422a, v8
	v_mul_f32_e32 v9, 0x3fcc422a, v9
	v_mul_f32_e32 v6, 0xbfb8aa3b, v6
	v_mul_f32_e32 v7, 0xbfb8aa3b, v7
	v_mul_f32_e32 v8, 0xbfb8aa3b, v8
	v_mul_f32_e32 v9, 0xbfb8aa3b, v9
	v_exp_f32_e32 v6, v6
	v_exp_f32_e32 v7, v7
	v_exp_f32_e32 v8, v8
	v_exp_f32_e32 v9, v9
	v_add_f32_e32 v6, 1.0, v6
	v_add_f32_e32 v7, 1.0, v7
	v_add_f32_e32 v8, 1.0, v8
	v_add_f32_e32 v9, 1.0, v9
	v_rcp_f32_e32 v6, v6
	v_rcp_f32_e32 v7, v7
	v_rcp_f32_e32 v8, v8
	v_rcp_f32_e32 v9, v9
	v_pk_mul_f32 v[2:3], v[2:3], v[6:7]
	s_nop 0
	v_cvt_pk_bf16_f32 v2, v2, v3
	v_pk_mul_f32 v[4:5], v[4:5], v[8:9]
	s_nop 0
	v_cvt_pk_bf16_f32 v3, v4, v5
	ds_write_b64 v67, v[2:3] offset:32
	flat_load_dwordx4 v[2:5], v[22:23] offset:96
	s_waitcnt vmcnt(0) lgkmcnt(0)
	v_pk_add_f32 v[2:3], v[14:15], v[2:3]
	v_pk_add_f32 v[4:5], v[16:17], v[4:5]
	v_mul_f32_e32 v6, 0x3d372713, v2
	v_mul_f32_e32 v7, 0x3d372713, v3
	v_mul_f32_e32 v8, 0x3d372713, v4
	v_mul_f32_e32 v9, 0x3d372713, v5
	v_mul_f32_e32 v6, v2, v6
	v_mul_f32_e32 v7, v3, v7
	v_mul_f32_e32 v8, v4, v8
	v_mul_f32_e32 v9, v5, v9
	v_fma_f32 v6, v2, v6, v2
	v_fma_f32 v7, v3, v7, v3
	v_fma_f32 v8, v4, v8, v4
	v_fma_f32 v9, v5, v9, v5
	v_mul_f32_e32 v6, 0x3fcc422a, v6
	v_mul_f32_e32 v7, 0x3fcc422a, v7
	v_mul_f32_e32 v8, 0x3fcc422a, v8
	v_mul_f32_e32 v9, 0x3fcc422a, v9
	v_mul_f32_e32 v6, 0xbfb8aa3b, v6
	v_mul_f32_e32 v7, 0xbfb8aa3b, v7
	v_mul_f32_e32 v8, 0xbfb8aa3b, v8
	v_mul_f32_e32 v9, 0xbfb8aa3b, v9
	v_exp_f32_e32 v6, v6
	v_exp_f32_e32 v7, v7
	v_exp_f32_e32 v8, v8
	v_exp_f32_e32 v9, v9
	v_add_f32_e32 v6, 1.0, v6
	v_add_f32_e32 v7, 1.0, v7
	v_add_f32_e32 v8, 1.0, v8
	v_add_f32_e32 v9, 1.0, v9
	v_rcp_f32_e32 v6, v6
	v_rcp_f32_e32 v7, v7
	v_rcp_f32_e32 v8, v8
	v_rcp_f32_e32 v9, v9
	v_pk_mul_f32 v[2:3], v[2:3], v[6:7]
	s_nop 0
	v_cvt_pk_bf16_f32 v2, v2, v3
	v_pk_mul_f32 v[4:5], v[4:5], v[8:9]
	s_nop 0
	v_cvt_pk_bf16_f32 v3, v4, v5
	ds_write_b64 v67, v[2:3] offset:48
	s_waitcnt lgkmcnt(0)
	s_barrier
	s_cbranch_vccz .LBB0_2144
	s_and_b64 s[4:5], s[4:5], exec
	s_mov_b32 s4, 0x680000
	s_cselect_b32 s96, s4, 0x684000
	v_lshl_add_u64 v[64:65], v[50:51], 0, s[96:97]
	flat_load_dwordx4 v[18:21], v[64:65]
	ds_read_b128 v[22:25], v68
	s_mov_b64 s[4:5], -1
	s_and_b64 vcc, exec, s[12:13]
	s_cbranch_vccz .LBB0_2150
	s_mov_b64 s[4:5], 0
	s_waitcnt vmcnt(0) lgkmcnt(0)
	v_mfma_f32_32x32x16_bf16 v[2:17], v[22:25], v[18:21], 0
